# S5 scan-loop rewrite (hoisted LDS reads, same f32 math), per-wave S5/zpost reorder, cg grid syncs replaced by flag+counter barrier and array census
# speedup vs baseline: 1.0145x; 1.0145x over previous
_Z14fwd_megakernel4Args:
	s_load_dword s3, s[0:1], 0x118
	s_add_u32 s4, s0, 0x118
	s_addc_u32 s5, s1, 0
	v_and_b32_e32 v6, 0x3ff, v0
	v_writelane_b32 v255, s4, 0
	v_readfirstlane_b32 s20, v6
	s_lshr_b32 s33, s20, 6
	v_writelane_b32 v255, s5, 1
	s_mov_b32 s4, 0
	v_writelane_b32 v255, s4, 45
	s_add_i32 s4, 0, 0x20000
	s_mov_b32 s16, s33
	s_mov_b32 s17, s2
	s_waitcnt lgkmcnt(0)
	s_mov_b32 s21, s3
	v_mov_b32_e32 v1, s4
	v_mbcnt_lo_u32_b32 v39, -1, 0
	v_mbcnt_hi_u32_b32 v39, -1, v39
	ds_read_b32 v1, v1
	s_add_i32 s4, 0, 0x20004
	s_waitcnt lgkmcnt(0)
	v_mov_b32_e32 v1, s4
	ds_read_b32 v1, v1
	s_add_i32 s4, 0, 0x20008
	s_waitcnt lgkmcnt(0)
	v_mov_b32_e32 v1, s4
	ds_read_b32 v1, v1
	s_cmp_eq_u32 s2, 0
	s_cselect_b64 s[4:5], -1, 0
	v_cmp_gt_u32_e32 vcc, 16, v6
	s_and_b64 s[8:9], s[4:5], vcc
	s_and_saveexec_b64 s[6:7], s[8:9]
	s_cbranch_execz .LBB0_2
	s_load_dwordx2 s[8:9], s[0:1], 0x110
	v_lshlrev_b32_e32 v2, 2, v6
	v_mov_b32_e32 v3, 0
	s_waitcnt lgkmcnt(0)
	v_lshl_add_u64 v[4:5], s[8:9], 0, v[2:3]
	v_add_co_u32_e32 v4, vcc, 0xdc000, v4
	s_nop 1
	v_addc_co_u32_e32 v5, vcc, 0, v5, vcc
	global_store_dword v[4:5], v3, off

.LBB0_221:
	v_readlane_b32 s10, v255, 45
	s_cmp_lt_u32 s33, 4
	s_cbranch_scc1 .Lro_s5
	s_cmp_lg_u32 s10, 0
	s_cbranch_scc1 .Lro_s5
	s_mov_b32 s10, 1
	v_writelane_b32 v255, s10, 45
	s_branch .LBB0_1461

.LBB0_1047:
	s_or_b64 exec, exec, s[30:31]
	s_waitcnt vmcnt(1)
	v_mfma_f32_16x16x32_bf16 v[108:111], v[0:3], v[52:55], 0
	v_cndmask_b32_e32 v99, v106, v107, vcc
	v_add_u32_e32 v106, s49, v99
	v_ashrrev_i32_e32 v107, 31, v106
	v_lshl_add_u64 v[106:107], v[106:107], 0, s[40:41]
	v_lshlrev_b64 v[106:107], 6, v[106:107]
	s_nop 2
	ds_write_b128 v102, v[108:111]
	v_mfma_f32_16x16x32_bf16 v[108:111], v[4:7], v[52:55], 0
	v_lshl_add_u64 v[106:107], v[90:91], 0, v[106:107]
	s_cmp_eq_u32 s50, s23
	s_nop 5
	ds_write_b128 v102, v[108:111] offset:64
	v_mfma_f32_16x16x32_bf16 v[108:111], v[8:11], v[52:55], 0
	s_nop 7
	ds_write_b128 v102, v[108:111] offset:128
	v_mfma_f32_16x16x32_bf16 v[108:111], v[12:15], v[52:55], 0
	s_nop 7
	ds_write_b128 v102, v[108:111] offset:192
	v_mfma_f32_16x16x32_bf16 v[108:111], v[16:19], v[52:55], 0
	s_nop 7
	ds_write_b128 v102, v[108:111] offset:256
	v_mfma_f32_16x16x32_bf16 v[108:111], v[20:23], v[52:55], 0
	s_nop 7
	ds_write_b128 v102, v[108:111] offset:320
	v_mfma_f32_16x16x32_bf16 v[108:111], v[24:27], v[52:55], 0
	v_mfma_f32_16x16x32_bf16 v[52:55], v[28:31], v[52:55], 0
	s_nop 6
	ds_write_b128 v102, v[108:111] offset:384
	ds_write_b128 v102, v[52:55] offset:448
	ds_read_b64 v[120:121], v103
	ds_read_b64 v[122:123], v103 offset:528
	ds_read_b64 v[124:125], v103 offset:1056
	ds_read_b64 v[126:127], v103 offset:1584
	ds_read_b64 v[128:129], v103 offset:2112
	ds_read_b64 v[130:131], v103 offset:2640
	ds_read_b64 v[132:133], v103 offset:3168
	ds_read_b64 v[134:135], v103 offset:3696
	ds_read_b64 v[136:137], v103 offset:4224
	ds_read_b64 v[138:139], v103 offset:4752
	ds_read_b64 v[140:141], v103 offset:5280
	ds_read_b64 v[142:143], v103 offset:5808
	ds_read_b64 v[144:145], v103 offset:6336
	ds_read_b64 v[146:147], v103 offset:6864
	ds_read_b64 v[148:149], v103 offset:7392
	ds_read_b64 v[150:151], v103 offset:7920
	s_waitcnt lgkmcnt(0)
	v_mul_f32_e32 v152, v84, v101
	v_mul_f32_e32 v153, v84, v100
	v_fma_f32 v152, v86, v100, -v152
	v_fma_f32 v153, v86, v101, v153
	v_add_f32_e32 v100, v152, v120
	v_add_f32_e32 v101, v153, v121
	v_cvt_pk_bf16_f32 v154, v100, v101
	ds_write_b32 v104, v154 offset:8448
	v_mul_f32_e32 v152, v84, v101
	v_mul_f32_e32 v153, v84, v100
	v_fma_f32 v152, v86, v100, -v152
	v_fma_f32 v153, v86, v101, v153
	v_add_f32_e32 v100, v152, v122
	v_add_f32_e32 v101, v153, v123
	v_cvt_pk_bf16_f32 v155, v100, v101
	ds_write_b32 v104, v155 offset:8720
	v_mul_f32_e32 v152, v84, v101
	v_mul_f32_e32 v153, v84, v100
	v_fma_f32 v152, v86, v100, -v152
	v_fma_f32 v153, v86, v101, v153
	v_add_f32_e32 v100, v152, v124
	v_add_f32_e32 v101, v153, v125
	v_cvt_pk_bf16_f32 v154, v100, v101
	ds_write_b32 v104, v154 offset:8992
	v_mul_f32_e32 v152, v84, v101
	v_mul_f32_e32 v153, v84, v100
	v_fma_f32 v152, v86, v100, -v152
	v_fma_f32 v153, v86, v101, v153
	v_add_f32_e32 v100, v152, v126
	v_add_f32_e32 v101, v153, v127
	v_cvt_pk_bf16_f32 v155, v100, v101
	ds_write_b32 v104, v155 offset:9264
	v_mul_f32_e32 v152, v84, v101
	v_mul_f32_e32 v153, v84, v100
	v_fma_f32 v152, v86, v100, -v152
	v_fma_f32 v153, v86, v101, v153
	v_add_f32_e32 v100, v152, v128
	v_add_f32_e32 v101, v153, v129
	v_cvt_pk_bf16_f32 v154, v100, v101
	ds_write_b32 v104, v154 offset:9536
	v_mul_f32_e32 v152, v84, v101
	v_mul_f32_e32 v153, v84, v100
	v_fma_f32 v152, v86, v100, -v152
	v_fma_f32 v153, v86, v101, v153
	v_add_f32_e32 v100, v152, v130
	v_add_f32_e32 v101, v153, v131
	v_cvt_pk_bf16_f32 v155, v100, v101
	ds_write_b32 v104, v155 offset:9808
	v_mul_f32_e32 v152, v84, v101
	v_mul_f32_e32 v153, v84, v100
	v_fma_f32 v152, v86, v100, -v152
	v_fma_f32 v153, v86, v101, v153
	v_add_f32_e32 v100, v152, v132
	v_add_f32_e32 v101, v153, v133
	v_cvt_pk_bf16_f32 v154, v100, v101
	ds_write_b32 v104, v154 offset:10080
	v_mul_f32_e32 v152, v84, v101
	v_mul_f32_e32 v153, v84, v100
	v_fma_f32 v152, v86, v100, -v152
	v_fma_f32 v153, v86, v101, v153
	v_add_f32_e32 v100, v152, v134
	v_add_f32_e32 v101, v153, v135
	v_cvt_pk_bf16_f32 v155, v100, v101
	ds_write_b32 v104, v155 offset:10352
	v_mul_f32_e32 v152, v84, v101
	v_mul_f32_e32 v153, v84, v100
	v_fma_f32 v152, v86, v100, -v152
	v_fma_f32 v153, v86, v101, v153
	v_add_f32_e32 v100, v152, v136
	v_add_f32_e32 v101, v153, v137
	v_cvt_pk_bf16_f32 v154, v100, v101
	ds_write_b32 v104, v154 offset:10624
	v_mul_f32_e32 v152, v84, v101
	v_mul_f32_e32 v153, v84, v100
	v_fma_f32 v152, v86, v100, -v152
	v_fma_f32 v153, v86, v101, v153
	v_add_f32_e32 v100, v152, v138
	v_add_f32_e32 v101, v153, v139
	v_cvt_pk_bf16_f32 v155, v100, v101
	ds_write_b32 v104, v155 offset:10896
	v_mul_f32_e32 v152, v84, v101
	v_mul_f32_e32 v153, v84, v100
	v_fma_f32 v152, v86, v100, -v152
	v_fma_f32 v153, v86, v101, v153
	v_add_f32_e32 v100, v152, v140
	v_add_f32_e32 v101, v153, v141
	v_cvt_pk_bf16_f32 v154, v100, v101
	ds_write_b32 v104, v154 offset:11168
	v_mul_f32_e32 v152, v84, v101
	v_mul_f32_e32 v153, v84, v100
	v_fma_f32 v152, v86, v100, -v152
	v_fma_f32 v153, v86, v101, v153
	v_add_f32_e32 v100, v152, v142
	v_add_f32_e32 v101, v153, v143
	v_cvt_pk_bf16_f32 v155, v100, v101
	ds_write_b32 v104, v155 offset:11440
	v_mul_f32_e32 v152, v84, v101
	v_mul_f32_e32 v153, v84, v100
	v_fma_f32 v152, v86, v100, -v152
	v_fma_f32 v153, v86, v101, v153
	v_add_f32_e32 v100, v152, v144
	v_add_f32_e32 v101, v153, v145
	v_cvt_pk_bf16_f32 v154, v100, v101
	ds_write_b32 v104, v154 offset:11712
	v_mul_f32_e32 v152, v84, v101
	v_mul_f32_e32 v153, v84, v100
	v_fma_f32 v152, v86, v100, -v152
	v_fma_f32 v153, v86, v101, v153
	v_add_f32_e32 v100, v152, v146
	v_add_f32_e32 v101, v153, v147
	v_cvt_pk_bf16_f32 v155, v100, v101
	ds_write_b32 v104, v155 offset:11984
	v_mul_f32_e32 v152, v84, v101
	v_mul_f32_e32 v153, v84, v100
	v_fma_f32 v152, v86, v100, -v152
	v_fma_f32 v153, v86, v101, v153
	v_add_f32_e32 v100, v152, v148
	v_add_f32_e32 v101, v153, v149
	v_cvt_pk_bf16_f32 v154, v100, v101
	ds_write_b32 v104, v154 offset:12256
	v_mul_f32_e32 v152, v84, v101
	v_mul_f32_e32 v153, v84, v100
	v_fma_f32 v152, v86, v100, -v152
	v_fma_f32 v153, v86, v101, v153
	v_add_f32_e32 v100, v152, v150
	v_add_f32_e32 v101, v153, v151
	v_cvt_pk_bf16_f32 v155, v100, v101
	ds_write_b32 v104, v155 offset:12528
	ds_read_b128 v[120:123], v105 offset:8448
	ds_read_b128 v[124:127], v105 offset:8512
	ds_read_b128 v[128:131], v105 offset:8576
	ds_read_b128 v[132:135], v105 offset:8640
	s_waitcnt lgkmcnt(3)
	v_mfma_f32_16x16x32_bf16 v[52:55], v[32:35], v[120:123], 0
	s_waitcnt lgkmcnt(2)
	v_mfma_f32_16x16x32_bf16 v[52:55], v[36:39], v[124:127], v[52:55]
	s_waitcnt lgkmcnt(1)
	v_mfma_f32_16x16x32_bf16 v[52:55], v[40:43], v[128:131], v[52:55]
	s_waitcnt lgkmcnt(0)
	v_mfma_f32_16x16x32_bf16 v[52:55], v[44:47], v[132:135], v[52:55]
	s_nop 7
	global_store_dwordx4 v[106:107], v[52:55], off
	s_cbranch_scc1 .LBB0_1049
	s_nop 0
	s_waitcnt vmcnt(1)
	v_mov_b64_e32 v[54:55], v[50:51]
	v_mov_b32_e32 v106, v98
	v_mov_b32_e32 v107, v97
	v_mov_b64_e32 v[52:53], v[48:49]
	s_branch .LBB0_1043

.LBB0_1457:
	s_or_b64 exec, exec, s[12:13]
	s_waitcnt vmcnt(1)
	v_mfma_f32_16x16x32_bf16 v[80:83], v[0:3], v[52:55], 0
	v_cndmask_b32_e32 v72, v73, v72, vcc
	v_add_u32_e32 v72, s17, v72
	v_ashrrev_i32_e32 v73, 31, v72
	v_lshl_add_u64 v[72:73], v[72:73], 0, s[40:41]
	v_lshlrev_b64 v[72:73], 6, v[72:73]
	s_nop 2
	ds_write_b128 v74, v[80:83]
	v_mfma_f32_16x16x32_bf16 v[80:83], v[4:7], v[52:55], 0
	v_lshl_add_u64 v[72:73], v[66:67], 0, v[72:73]
	s_cmp_eq_u32 s14, s23
	s_nop 5
	ds_write_b128 v74, v[80:83] offset:64
	v_mfma_f32_16x16x32_bf16 v[80:83], v[8:11], v[52:55], 0
	s_nop 7
	ds_write_b128 v74, v[80:83] offset:128
	v_mfma_f32_16x16x32_bf16 v[80:83], v[12:15], v[52:55], 0
	s_nop 7
	ds_write_b128 v74, v[80:83] offset:192
	v_mfma_f32_16x16x32_bf16 v[80:83], v[16:19], v[52:55], 0
	s_nop 7
	ds_write_b128 v74, v[80:83] offset:256
	v_mfma_f32_16x16x32_bf16 v[80:83], v[20:23], v[52:55], 0
	s_nop 7
	ds_write_b128 v74, v[80:83] offset:320
	v_mfma_f32_16x16x32_bf16 v[80:83], v[24:27], v[52:55], 0
	v_mfma_f32_16x16x32_bf16 v[52:55], v[28:31], v[52:55], 0
	s_nop 6
	ds_write_b128 v74, v[80:83] offset:384
	ds_write_b128 v74, v[52:55] offset:448
	ds_read_b64 v[120:121], v75
	ds_read_b64 v[122:123], v75 offset:528
	ds_read_b64 v[124:125], v75 offset:1056
	ds_read_b64 v[126:127], v75 offset:1584
	ds_read_b64 v[128:129], v75 offset:2112
	ds_read_b64 v[130:131], v75 offset:2640
	ds_read_b64 v[132:133], v75 offset:3168
	ds_read_b64 v[134:135], v75 offset:3696
	ds_read_b64 v[136:137], v75 offset:4224
	ds_read_b64 v[138:139], v75 offset:4752
	ds_read_b64 v[140:141], v75 offset:5280
	ds_read_b64 v[142:143], v75 offset:5808
	ds_read_b64 v[144:145], v75 offset:6336
	ds_read_b64 v[146:147], v75 offset:6864
	ds_read_b64 v[148:149], v75 offset:7392
	ds_read_b64 v[150:151], v75 offset:7920
	s_waitcnt lgkmcnt(0)
	v_mul_f32_e32 v152, v58, v63
	v_mul_f32_e32 v153, v58, v62
	v_fma_f32 v152, v60, v62, -v152
	v_fma_f32 v153, v60, v63, v153
	v_add_f32_e32 v62, v152, v120
	v_add_f32_e32 v63, v153, v121
	v_cvt_pk_bf16_f32 v154, v62, v63
	ds_write_b32 v76, v154 offset:8448
	v_mul_f32_e32 v152, v58, v63
	v_mul_f32_e32 v153, v58, v62
	v_fma_f32 v152, v60, v62, -v152
	v_fma_f32 v153, v60, v63, v153
	v_add_f32_e32 v62, v152, v122
	v_add_f32_e32 v63, v153, v123
	v_cvt_pk_bf16_f32 v155, v62, v63
	ds_write_b32 v76, v155 offset:8720
	v_mul_f32_e32 v152, v58, v63
	v_mul_f32_e32 v153, v58, v62
	v_fma_f32 v152, v60, v62, -v152
	v_fma_f32 v153, v60, v63, v153
	v_add_f32_e32 v62, v152, v124
	v_add_f32_e32 v63, v153, v125
	v_cvt_pk_bf16_f32 v154, v62, v63
	ds_write_b32 v76, v154 offset:8992
	v_mul_f32_e32 v152, v58, v63
	v_mul_f32_e32 v153, v58, v62
	v_fma_f32 v152, v60, v62, -v152
	v_fma_f32 v153, v60, v63, v153
	v_add_f32_e32 v62, v152, v126
	v_add_f32_e32 v63, v153, v127
	v_cvt_pk_bf16_f32 v155, v62, v63
	ds_write_b32 v76, v155 offset:9264
	v_mul_f32_e32 v152, v58, v63
	v_mul_f32_e32 v153, v58, v62
	v_fma_f32 v152, v60, v62, -v152
	v_fma_f32 v153, v60, v63, v153
	v_add_f32_e32 v62, v152, v128
	v_add_f32_e32 v63, v153, v129
	v_cvt_pk_bf16_f32 v154, v62, v63
	ds_write_b32 v76, v154 offset:9536
	v_mul_f32_e32 v152, v58, v63
	v_mul_f32_e32 v153, v58, v62
	v_fma_f32 v152, v60, v62, -v152
	v_fma_f32 v153, v60, v63, v153
	v_add_f32_e32 v62, v152, v130
	v_add_f32_e32 v63, v153, v131
	v_cvt_pk_bf16_f32 v155, v62, v63
	ds_write_b32 v76, v155 offset:9808
	v_mul_f32_e32 v152, v58, v63
	v_mul_f32_e32 v153, v58, v62
	v_fma_f32 v152, v60, v62, -v152
	v_fma_f32 v153, v60, v63, v153
	v_add_f32_e32 v62, v152, v132
	v_add_f32_e32 v63, v153, v133
	v_cvt_pk_bf16_f32 v154, v62, v63
	ds_write_b32 v76, v154 offset:10080
	v_mul_f32_e32 v152, v58, v63
	v_mul_f32_e32 v153, v58, v62
	v_fma_f32 v152, v60, v62, -v152
	v_fma_f32 v153, v60, v63, v153
	v_add_f32_e32 v62, v152, v134
	v_add_f32_e32 v63, v153, v135
	v_cvt_pk_bf16_f32 v155, v62, v63
	ds_write_b32 v76, v155 offset:10352
	v_mul_f32_e32 v152, v58, v63
	v_mul_f32_e32 v153, v58, v62
	v_fma_f32 v152, v60, v62, -v152
	v_fma_f32 v153, v60, v63, v153
	v_add_f32_e32 v62, v152, v136
	v_add_f32_e32 v63, v153, v137
	v_cvt_pk_bf16_f32 v154, v62, v63
	ds_write_b32 v76, v154 offset:10624
	v_mul_f32_e32 v152, v58, v63
	v_mul_f32_e32 v153, v58, v62
	v_fma_f32 v152, v60, v62, -v152
	v_fma_f32 v153, v60, v63, v153
	v_add_f32_e32 v62, v152, v138
	v_add_f32_e32 v63, v153, v139
	v_cvt_pk_bf16_f32 v155, v62, v63
	ds_write_b32 v76, v155 offset:10896
	v_mul_f32_e32 v152, v58, v63
	v_mul_f32_e32 v153, v58, v62
	v_fma_f32 v152, v60, v62, -v152
	v_fma_f32 v153, v60, v63, v153
	v_add_f32_e32 v62, v152, v140
	v_add_f32_e32 v63, v153, v141
	v_cvt_pk_bf16_f32 v154, v62, v63
	ds_write_b32 v76, v154 offset:11168
	v_mul_f32_e32 v152, v58, v63
	v_mul_f32_e32 v153, v58, v62
	v_fma_f32 v152, v60, v62, -v152
	v_fma_f32 v153, v60, v63, v153
	v_add_f32_e32 v62, v152, v142
	v_add_f32_e32 v63, v153, v143
	v_cvt_pk_bf16_f32 v155, v62, v63
	ds_write_b32 v76, v155 offset:11440
	v_mul_f32_e32 v152, v58, v63
	v_mul_f32_e32 v153, v58, v62
	v_fma_f32 v152, v60, v62, -v152
	v_fma_f32 v153, v60, v63, v153
	v_add_f32_e32 v62, v152, v144
	v_add_f32_e32 v63, v153, v145
	v_cvt_pk_bf16_f32 v154, v62, v63
	ds_write_b32 v76, v154 offset:11712
	v_mul_f32_e32 v152, v58, v63
	v_mul_f32_e32 v153, v58, v62
	v_fma_f32 v152, v60, v62, -v152
	v_fma_f32 v153, v60, v63, v153
	v_add_f32_e32 v62, v152, v146
	v_add_f32_e32 v63, v153, v147
	v_cvt_pk_bf16_f32 v155, v62, v63
	ds_write_b32 v76, v155 offset:11984
	v_mul_f32_e32 v152, v58, v63
	v_mul_f32_e32 v153, v58, v62
	v_fma_f32 v152, v60, v62, -v152
	v_fma_f32 v153, v60, v63, v153
	v_add_f32_e32 v62, v152, v148
	v_add_f32_e32 v63, v153, v149
	v_cvt_pk_bf16_f32 v154, v62, v63
	ds_write_b32 v76, v154 offset:12256
	v_mul_f32_e32 v152, v58, v63
	v_mul_f32_e32 v153, v58, v62
	v_fma_f32 v152, v60, v62, -v152
	v_fma_f32 v153, v60, v63, v153
	v_add_f32_e32 v62, v152, v150
	v_add_f32_e32 v63, v153, v151
	v_cvt_pk_bf16_f32 v155, v62, v63
	ds_write_b32 v76, v155 offset:12528
	ds_read_b128 v[120:123], v77 offset:8448
	ds_read_b128 v[124:127], v77 offset:8512
	ds_read_b128 v[128:131], v77 offset:8576
	ds_read_b128 v[132:135], v77 offset:8640
	s_waitcnt lgkmcnt(3)
	v_mfma_f32_16x16x32_bf16 v[52:55], v[32:35], v[120:123], 0
	s_waitcnt lgkmcnt(2)
	v_mfma_f32_16x16x32_bf16 v[52:55], v[36:39], v[124:127], v[52:55]
	s_waitcnt lgkmcnt(1)
	v_mfma_f32_16x16x32_bf16 v[52:55], v[40:43], v[128:131], v[52:55]
	s_waitcnt lgkmcnt(0)
	v_mfma_f32_16x16x32_bf16 v[52:55], v[44:47], v[132:135], v[52:55]
	s_nop 7
	global_store_dwordx4 v[72:73], v[52:55], off
	s_cbranch_scc1 .LBB0_1459
	s_nop 0
	s_waitcnt vmcnt(1)
	v_mov_b64_e32 v[54:55], v[50:51]
	v_mov_b32_e32 v73, v79
	v_mov_b32_e32 v72, v78
	v_mov_b64_e32 v[52:53], v[48:49]
	s_branch .LBB0_1453

.LBB0_1461:
	v_readlane_b32 s12, v255, 45
	s_cmp_lg_u32 s12, 2
	s_cbranch_scc1 .Lro_zp
	s_mov_b32 s12, 0
	v_writelane_b32 v255, s12, 45
	s_branch .LBB0_1489

.LBB0_1489:
	v_readlane_b32 vcc_lo, v255, 45
	s_cmp_lg_u32 vcc_lo, 1
	s_cbranch_scc1 .Lro_seam
	s_mov_b32 vcc_lo, 2
	v_writelane_b32 v255, vcc_lo, 45
	s_branch .LBB0_221
